# attention: keep-test on per-half row max with rare path out of line (no cross-half permlane/exp/cndmask in common path); per-half l accumulation reduced once per unit
# speedup vs baseline: 1.0907x; 1.0007x over previous
.LBB0_218:
	s_add_i32 s20, s76, 1
	s_cmp_lg_u32 s76, 2
	s_cselect_b32 s77, s20, 0
	s_lshl_b32 s46, s76, 14
	s_add_i32 s20, s46, 0xffffc000
	s_cmp_lg_u32 s76, 0
	s_cselect_b32 s47, s20, 0x8000
	s_add_i32 s20, s47, s71
	s_mov_b32 s21, m0
	s_mov_b32 m0, s20
	s_nop 0
	global_load_lds_dwordx4 v184, s[82:83]
	s_mov_b32 m0, s21
	s_addk_i32 s20, 0x2000
	s_add_u32 s79, s73, 0x800
	s_addc_u32 s81, s74, 0
	s_mov_b32 s21, m0
	s_mov_b32 m0, s20
	s_nop 0
	global_load_lds_dwordx4 v186, s[82:83]
	s_mov_b32 m0, s21
	s_add_u32 s20, s73, 0xc0800
	s_addc_u32 s21, s74, 0
	s_lshl_b32 s78, s77, 14
	s_add_i32 s76, s78, s72
	s_mov_b32 s84, m0
	s_mov_b32 m0, s76
	s_nop 0
	global_load_lds_dwordx4 v185, s[20:21]
	s_mov_b32 m0, s84
	s_addk_i32 s76, 0x2000
	s_mov_b32 s84, m0
	s_mov_b32 m0, s76
	s_nop 0
	global_load_lds_dwordx4 v187, s[20:21]
	s_mov_b32 m0, s84
	v_add_u32_e32 v104, s46, v189
	v_add_u32_e32 v100, v104, v210
	v_add_u32_e32 v105, v104, v212
	ds_read_b128 v[96:99], v100
	ds_read_b128 v[100:103], v100 offset:8192
	ds_read_b128 v[144:147], v105
	ds_read_b128 v[148:151], v105 offset:8192
	v_add_u32_e32 v105, v104, v214
	v_add_u32_e32 v104, v104, v216
	ds_read_b128 v[152:155], v105
	ds_read_b128 v[222:225], v105 offset:8192
	ds_read_b128 v[156:159], v104
	ds_read_b128 v[226:229], v104 offset:8192
	v_add_f32_e32 v104, 0, v80
	v_add_f32_e32 v104, v81, v104
	v_add_f32_e32 v104, v82, v104
	v_add_f32_e32 v104, v83, v104
	v_add_f32_e32 v104, v84, v104
	v_add_f32_e32 v104, v85, v104
	v_add_f32_e32 v104, v86, v104
	v_add_f32_e32 v104, v87, v104
	s_nop 0
	v_add_f32_e32 v104, v88, v104
	s_waitcnt lgkmcnt(7)
	v_mfma_f32_32x32x16_bf16 v[112:127], v[96:99], v[140:143], 0
	v_add_f32_e32 v104, v89, v104
	v_add_f32_e32 v104, v90, v104
	v_add_f32_e32 v104, v91, v104
	v_add_f32_e32 v104, v92, v104
	v_add_f32_e32 v104, v93, v104
	v_add_f32_e32 v104, v94, v104
	v_add_f32_e32 v104, v95, v104
	s_nop 0
	v_add_f32_e32 v96, v64, v104
	v_add_f32_e32 v96, v65, v96
	v_add_f32_e32 v96, v66, v96
	v_add_f32_e32 v96, v67, v96
	v_add_f32_e32 v96, v68, v96
	v_add_f32_e32 v96, v69, v96
	v_add_f32_e32 v96, v70, v96
	v_add_f32_e32 v196, v71, v96
	s_waitcnt lgkmcnt(6)
	v_mfma_f32_32x32x16_bf16 v[96:111], v[100:103], v[140:143], 0
	s_nop 0
	v_add_f32_e32 v196, v72, v196
	s_waitcnt lgkmcnt(5)
	v_mfma_f32_32x32x16_bf16 v[112:127], v[144:147], v[136:139], v[112:127]
	v_add_f32_e32 v196, v73, v196
	v_add_f32_e32 v196, v74, v196
	v_add_f32_e32 v196, v75, v196
	v_add_f32_e32 v196, v76, v196
	v_add_f32_e32 v196, v77, v196
	v_add_f32_e32 v196, v78, v196
	v_add_f32_e32 v196, v79, v196
	v_mov_b32_e32 v221, v196
	v_cvt_pk_bf16_f32 v144, v80, v81
	v_cvt_pk_bf16_f32 v145, v82, v83
	v_cvt_pk_bf16_f32 v146, v84, v85
	v_cvt_pk_bf16_f32 v147, v86, v87
	v_fmac_f32_e32 v221, v219, v220
	v_cvt_pk_bf16_f32 v84, v88, v89
	v_cvt_pk_bf16_f32 v85, v90, v91
	v_cvt_pk_bf16_f32 v86, v92, v93
	v_cvt_pk_bf16_f32 v87, v94, v95
	v_cvt_pk_bf16_f32 v80, v64, v65
	v_cvt_pk_bf16_f32 v81, v66, v67
	v_cvt_pk_bf16_f32 v82, v68, v69
	v_cvt_pk_bf16_f32 v83, v70, v71
	v_cvt_pk_bf16_f32 v64, v72, v73
	v_cvt_pk_bf16_f32 v65, v74, v75
	v_cvt_pk_bf16_f32 v66, v76, v77
	v_cvt_pk_bf16_f32 v67, v78, v79
	s_waitcnt lgkmcnt(4)
	v_mfma_f32_32x32x16_bf16 v[96:111], v[148:151], v[136:139], v[96:111]
	v_add_u32_e32 v196, s47, v217
	s_waitcnt lgkmcnt(3)
	v_mfma_f32_32x32x16_bf16 v[112:127], v[152:155], v[132:135], v[112:127]
	ds_read_b64_tr_b16 v[72:73], v196
	ds_read_b64_tr_b16 v[88:89], v196 offset:512
	ds_read_b64_tr_b16 v[152:153], v196 offset:1024
	ds_read_b64_tr_b16 v[230:231], v196 offset:1536
	ds_read_b64_tr_b16 v[74:75], v196 offset:2048
	ds_read_b64_tr_b16 v[90:91], v196 offset:2560
	ds_read_b64_tr_b16 v[154:155], v196 offset:3072
	ds_read_b64_tr_b16 v[232:233], v196 offset:3584
	s_waitcnt lgkmcnt(10)
	v_mfma_f32_32x32x16_bf16 v[96:111], v[222:225], v[132:135], v[96:111]
	s_waitcnt lgkmcnt(9)
	v_mfma_f32_32x32x16_bf16 v[112:127], v[156:159], v[128:131], v[112:127]
	ds_read_b64_tr_b16 v[234:235], v196 offset:4096
	ds_read_b64_tr_b16 v[238:239], v196 offset:4608
	ds_read_b64_tr_b16 v[242:243], v196 offset:5120
	ds_read_b64_tr_b16 v[156:157], v196 offset:5632
	ds_read_b64_tr_b16 v[236:237], v196 offset:6144
	ds_read_b64_tr_b16 v[240:241], v196 offset:6656
	ds_read_b64_tr_b16 v[244:245], v196 offset:7168
	ds_read_b64_tr_b16 v[158:159], v196 offset:7680
	ds_read_b64_tr_b16 v[148:149], v196 offset:8192
	ds_read_b64_tr_b16 v[92:93], v196 offset:8704
	ds_read_b64_tr_b16 v[76:77], v196 offset:9216
	ds_read_b64_tr_b16 v[68:69], v196 offset:9728
	ds_read_b64_tr_b16 v[150:151], v196 offset:10240
	ds_read_b64_tr_b16 v[94:95], v196 offset:10752
	ds_read_b64_tr_b16 v[78:79], v196 offset:11264
	ds_read_b64_tr_b16 v[70:71], v196 offset:11776
	s_waitcnt lgkmcnt(14)
	v_mfma_f32_32x32x16_bf16 v[96:111], v[226:229], v[128:131], v[96:111]
	v_mfma_f32_32x32x16_bf16 v[0:15], v[144:147], v[72:75], v[0:15]
	v_max3_f32 v72, v112, v113, v114
	v_max3_f32 v72, v72, v115, v116
	v_max3_f32 v72, v72, v117, v118
	v_max3_f32 v72, v72, v119, v120
	v_mfma_f32_32x32x16_bf16 v[48:63], v[144:147], v[88:91], v[48:63]
	v_max3_f32 v72, v72, v121, v122
	v_max3_f32 v72, v72, v123, v124
	v_max3_f32 v72, v72, v125, v126
	s_nop 2
	v_max3_f32 v72, v72, v127, v96
	v_mfma_f32_32x32x16_bf16 v[32:47], v[144:147], v[152:155], v[32:47]
	v_max3_f32 v72, v72, v97, v98
	v_max3_f32 v72, v72, v99, v100
	v_max3_f32 v72, v72, v101, v102
	v_max3_f32 v72, v72, v103, v104
	v_mfma_f32_32x32x16_bf16 v[16:31], v[144:147], v[230:233], v[16:31]
	v_max_f32_e32 v72, v72, v72
	v_max_f32_e32 v73, v105, v105
	v_max_f32_e32 v72, v72, v73
	v_max3_f32 v72, v72, v106, v107
	v_max3_f32 v72, v72, v108, v109
	v_max3_f32 v197, v72, v110, v111
	ds_read_b64_tr_b16 v[152:153], v196 offset:12288
	ds_read_b64_tr_b16 v[144:145], v196 offset:12800
	ds_read_b64_tr_b16 v[88:89], v196 offset:13312
	ds_read_b64_tr_b16 v[72:73], v196 offset:13824
	ds_read_b64_tr_b16 v[154:155], v196 offset:14336
	ds_read_b64_tr_b16 v[146:147], v196 offset:14848
	ds_read_b64_tr_b16 v[90:91], v196 offset:15360
	ds_read_b64_tr_b16 v[74:75], v196 offset:15872
	v_sub_f32_e32 v196, v197, v218
	v_cmp_ge_f32_e32 vcc, s6, v196
	s_cmp_eq_u64 vcc, exec
	s_cbranch_scc0 .Latt_rare_1
	v_mov_b32_e32 v220, v218
	v_mov_b32_e32 v196, v218
	v_mov_b32_e32 v218, 1.0
.Latt_back_1:
	s_waitcnt lgkmcnt(14)
	v_mfma_f32_32x32x16_bf16 v[0:15], v[84:87], v[234:237], v[0:15]
	v_mfma_f32_32x32x16_bf16 v[48:63], v[84:87], v[238:241], v[48:63]
	v_sub_f32_e32 v113, v113, v196
	v_sub_f32_e32 v112, v112, v196
	v_add_f32_e64 v114, v114, -v196
	v_add_f32_e64 v115, v115, -v196
	v_add_f32_e64 v116, v116, -v196
	v_add_f32_e64 v117, v117, -v196
	v_pk_add_f32 v[118:119], v[118:119], v[196:197] op_sel_hi:[1,0] neg_lo:[0,1] neg_hi:[0,1]
	s_nop 0
	v_mfma_f32_32x32x16_bf16 v[32:47], v[84:87], v[242:245], v[32:47]
	v_add_f32_e64 v120, v120, -v196
	v_add_f32_e64 v121, v121, -v196
	v_add_f32_e64 v122, v122, -v196
	v_add_f32_e64 v123, v123, -v196
	v_add_f32_e64 v124, v124, -v196
	v_add_f32_e64 v125, v125, -v196
	v_pk_add_f32 v[126:127], v[126:127], v[196:197] op_sel_hi:[1,0] neg_lo:[0,1] neg_hi:[0,1]
	s_nop 0
	v_mfma_f32_32x32x16_bf16 v[16:31], v[84:87], v[156:159], v[16:31]
	v_sub_f32_e32 v97, v97, v196
	v_sub_f32_e32 v96, v96, v196
	v_add_f32_e64 v98, v98, -v196
	v_add_f32_e64 v99, v99, -v196
	v_add_f32_e64 v100, v100, -v196
	v_add_f32_e64 v101, v101, -v196
	v_pk_add_f32 v[102:103], v[102:103], v[196:197] op_sel_hi:[1,0] neg_lo:[0,1] neg_hi:[0,1]
	s_nop 0
	s_waitcnt lgkmcnt(11)
	v_mfma_f32_32x32x16_bf16 v[0:15], v[80:83], v[148:151], v[0:15]
	v_add_f32_e64 v104, v104, -v196
	v_add_f32_e64 v105, v105, -v196
	v_add_f32_e64 v106, v106, -v196
	v_add_f32_e64 v107, v107, -v196
	v_add_f32_e64 v108, v108, -v196
	v_add_f32_e64 v109, v109, -v196
	v_pk_add_f32 v[110:111], v[110:111], v[196:197] op_sel_hi:[1,0] neg_lo:[0,1] neg_hi:[0,1]
	s_nop 0
	s_waitcnt lgkmcnt(10)
	v_mfma_f32_32x32x16_bf16 v[48:63], v[80:83], v[92:95], v[48:63]
	v_exp_f32_e32 v112, v112
	v_exp_f32_e32 v113, v113
	v_exp_f32_e32 v114, v114
	v_exp_f32_e32 v115, v115
	s_waitcnt lgkmcnt(9)
	v_mfma_f32_32x32x16_bf16 v[32:47], v[80:83], v[76:79], v[32:47]
	v_exp_f32_e32 v116, v116
	v_exp_f32_e32 v117, v117
	v_exp_f32_e32 v118, v118
	v_exp_f32_e32 v119, v119
	s_waitcnt lgkmcnt(8)
	v_mfma_f32_32x32x16_bf16 v[16:31], v[80:83], v[68:71], v[16:31]
	v_exp_f32_e32 v120, v120
	v_exp_f32_e32 v121, v121
	v_exp_f32_e32 v122, v122
	v_exp_f32_e32 v123, v123
	s_waitcnt lgkmcnt(3)
	v_mfma_f32_32x32x16_bf16 v[0:15], v[64:67], v[152:155], v[0:15]
	v_exp_f32_e32 v124, v124
	v_exp_f32_e32 v125, v125
	v_exp_f32_e32 v126, v126
	v_exp_f32_e32 v127, v127
	s_waitcnt lgkmcnt(2)
	v_mfma_f32_32x32x16_bf16 v[48:63], v[64:67], v[144:147], v[48:63]
	v_exp_f32_e32 v96, v96
	v_exp_f32_e32 v97, v97
	v_exp_f32_e32 v98, v98
	v_exp_f32_e32 v99, v99
	v_exp_f32_e32 v100, v100
	s_waitcnt lgkmcnt(1)
	v_mfma_f32_32x32x16_bf16 v[32:47], v[64:67], v[88:91], v[32:47]
	v_exp_f32_e32 v101, v101
	v_exp_f32_e32 v102, v102
	v_exp_f32_e32 v103, v103
	v_exp_f32_e32 v104, v104
	v_exp_f32_e32 v105, v105
	s_waitcnt lgkmcnt(0)
	v_mfma_f32_32x32x16_bf16 v[16:31], v[64:67], v[72:75], v[16:31]
	v_exp_f32_e32 v106, v106
	v_exp_f32_e32 v107, v107
	v_exp_f32_e32 v108, v108
	v_exp_f32_e32 v109, v109
	v_exp_f32_e32 v110, v110
	v_exp_f32_e32 v111, v111
	v_cmp_gt_f32_e32 vcc, 1.0, v218
	s_cbranch_vccz .LBB0_222
	s_and_saveexec_b64 s[20:21], s[38:39]
	ds_write_b32 v182, v218 offset:128
	s_or_b64 exec, exec, s[20:21]
	s_waitcnt lgkmcnt(0)
	v_add_u32_e32 v76, s70, v162
	ds_read_b128 v[64:67], v76 offset:224
	ds_read_b128 v[68:71], v76 offset:192
	ds_read_b128 v[72:75], v76 offset:160
	ds_read_b128 v[76:79], v76 offset:128
	s_waitcnt lgkmcnt(3)
	v_pk_mul_f32 v[12:13], v[12:13], v[64:65]
	s_waitcnt lgkmcnt(2)
	v_pk_mul_f32 v[8:9], v[8:9], v[68:69]
	s_waitcnt lgkmcnt(1)
	v_pk_mul_f32 v[4:5], v[4:5], v[72:73]
	v_pk_mul_f32 v[14:15], v[14:15], v[66:67]
	v_pk_mul_f32 v[10:11], v[10:11], v[70:71]
	v_pk_mul_f32 v[6:7], v[6:7], v[74:75]
	s_waitcnt lgkmcnt(0)
	v_pk_mul_f32 v[2:3], v[2:3], v[78:79]
	v_pk_mul_f32 v[0:1], v[0:1], v[76:77]
	v_pk_mul_f32 v[60:61], v[60:61], v[64:65]
	v_pk_mul_f32 v[56:57], v[56:57], v[68:69]
	v_pk_mul_f32 v[52:53], v[52:53], v[72:73]
	v_pk_mul_f32 v[62:63], v[62:63], v[66:67]
	v_pk_mul_f32 v[58:59], v[58:59], v[70:71]
	v_pk_mul_f32 v[54:55], v[54:55], v[74:75]
	v_pk_mul_f32 v[50:51], v[50:51], v[78:79]
	v_pk_mul_f32 v[48:49], v[48:49], v[76:77]
	v_pk_mul_f32 v[44:45], v[44:45], v[64:65]
	v_pk_mul_f32 v[40:41], v[40:41], v[68:69]
	v_pk_mul_f32 v[36:37], v[36:37], v[72:73]
	v_pk_mul_f32 v[46:47], v[46:47], v[66:67]
	v_pk_mul_f32 v[42:43], v[42:43], v[70:71]
	v_pk_mul_f32 v[38:39], v[38:39], v[74:75]
	v_pk_mul_f32 v[34:35], v[34:35], v[78:79]
	v_pk_mul_f32 v[32:33], v[32:33], v[76:77]
	v_pk_mul_f32 v[28:29], v[28:29], v[64:65]
	v_pk_mul_f32 v[24:25], v[24:25], v[68:69]
	v_pk_mul_f32 v[20:21], v[20:21], v[72:73]
	v_pk_mul_f32 v[30:31], v[30:31], v[66:67]
	v_pk_mul_f32 v[26:27], v[26:27], v[70:71]
	v_pk_mul_f32 v[22:23], v[22:23], v[74:75]
	v_pk_mul_f32 v[18:19], v[18:19], v[78:79]
	v_pk_mul_f32 v[16:17], v[16:17], v[76:77]

.LBB0_226:
	s_add_i32 s20, s77, 1
	s_cmp_lg_u32 s77, 2
	s_cselect_b32 s76, s20, 0
	s_lshl_b32 s20, s76, 14
	s_add_i32 s46, s20, s72
	s_add_i32 s47, s46, 0x2000
	s_add_u32 s20, s79, 0x180000
	s_addc_u32 s21, s81, 0
	s_mov_b32 s77, m0
	s_mov_b32 m0, s46
	s_nop 0
	global_load_lds_dwordx4 v185, s[20:21]
	s_mov_b32 m0, s77
	s_mov_b32 s46, m0
	s_mov_b32 m0, s47
	s_nop 0
	global_load_lds_dwordx4 v187, s[20:21]
	s_mov_b32 m0, s46
	v_add_u32_e32 v72, s78, v189
	v_add_u32_e32 v68, v72, v210
	v_add_u32_e32 v73, v72, v212
	ds_read_b128 v[64:67], v68
	ds_read_b128 v[68:71], v68 offset:8192
	ds_read_b128 v[144:147], v73
	ds_read_b128 v[148:151], v73 offset:8192
	v_add_u32_e32 v73, v72, v214
	v_add_u32_e32 v72, v72, v216
	ds_read_b128 v[152:155], v73
	ds_read_b128 v[222:225], v73 offset:8192
	ds_read_b128 v[156:159], v72
	ds_read_b128 v[226:229], v72 offset:8192
	v_add_f32_e32 v72, 0, v112
	v_add_f32_e32 v72, v113, v72
	v_add_f32_e32 v72, v114, v72
	v_add_f32_e32 v72, v115, v72
	v_add_f32_e32 v72, v116, v72
	v_add_f32_e32 v72, v117, v72
	v_add_f32_e32 v72, v118, v72
	v_add_f32_e32 v72, v119, v72
	s_nop 0
	v_add_f32_e32 v72, v120, v72
	s_waitcnt lgkmcnt(7)
	v_mfma_f32_32x32x16_bf16 v[80:95], v[64:67], v[140:143], 0
	v_add_f32_e32 v72, v121, v72
	v_add_f32_e32 v72, v122, v72
	v_add_f32_e32 v72, v123, v72
	v_add_f32_e32 v72, v124, v72
	v_add_f32_e32 v72, v125, v72
	v_add_f32_e32 v72, v126, v72
	v_add_f32_e32 v72, v127, v72
	s_nop 0
	v_add_f32_e32 v64, v96, v72
	v_add_f32_e32 v64, v97, v64
	v_add_f32_e32 v64, v98, v64
	v_add_f32_e32 v64, v99, v64
	v_add_f32_e32 v64, v100, v64
	v_add_f32_e32 v64, v101, v64
	v_add_f32_e32 v64, v102, v64
	v_add_f32_e32 v196, v103, v64
	s_waitcnt lgkmcnt(6)
	v_mfma_f32_32x32x16_bf16 v[64:79], v[68:71], v[140:143], 0
	s_nop 0
	v_add_f32_e32 v196, v104, v196
	s_waitcnt lgkmcnt(5)
	v_mfma_f32_32x32x16_bf16 v[80:95], v[144:147], v[136:139], v[80:95]
	v_add_f32_e32 v196, v105, v196
	v_add_f32_e32 v196, v106, v196
	v_add_f32_e32 v196, v107, v196
	v_add_f32_e32 v196, v108, v196
	v_add_f32_e32 v196, v109, v196
	v_add_f32_e32 v196, v110, v196
	v_add_f32_e32 v196, v111, v196
	v_mov_b32_e32 v219, v196
	v_cvt_pk_bf16_f32 v144, v112, v113
	v_cvt_pk_bf16_f32 v145, v114, v115
	v_cvt_pk_bf16_f32 v146, v116, v117
	v_cvt_pk_bf16_f32 v147, v118, v119
	v_fmac_f32_e32 v219, v221, v218
	v_cvt_pk_bf16_f32 v116, v120, v121
	v_cvt_pk_bf16_f32 v117, v122, v123
	v_cvt_pk_bf16_f32 v118, v124, v125
	v_cvt_pk_bf16_f32 v119, v126, v127
	v_cvt_pk_bf16_f32 v112, v96, v97
	v_cvt_pk_bf16_f32 v113, v98, v99
	v_cvt_pk_bf16_f32 v114, v100, v101
	v_cvt_pk_bf16_f32 v115, v102, v103
	v_cvt_pk_bf16_f32 v96, v104, v105
	v_cvt_pk_bf16_f32 v97, v106, v107
	v_cvt_pk_bf16_f32 v98, v108, v109
	v_cvt_pk_bf16_f32 v99, v110, v111
	s_waitcnt lgkmcnt(4)
	v_mfma_f32_32x32x16_bf16 v[64:79], v[148:151], v[136:139], v[64:79]
	v_add_u32_e32 v196, s86, v217
	s_waitcnt lgkmcnt(3)
	v_mfma_f32_32x32x16_bf16 v[80:95], v[152:155], v[132:135], v[80:95]
	ds_read_b64_tr_b16 v[104:105], v196
	ds_read_b64_tr_b16 v[120:121], v196 offset:512
	ds_read_b64_tr_b16 v[152:153], v196 offset:1024
	ds_read_b64_tr_b16 v[230:231], v196 offset:1536
	ds_read_b64_tr_b16 v[106:107], v196 offset:2048
	ds_read_b64_tr_b16 v[122:123], v196 offset:2560
	ds_read_b64_tr_b16 v[154:155], v196 offset:3072
	ds_read_b64_tr_b16 v[232:233], v196 offset:3584
	s_waitcnt lgkmcnt(10)
	v_mfma_f32_32x32x16_bf16 v[64:79], v[222:225], v[132:135], v[64:79]
	s_waitcnt lgkmcnt(9)
	v_mfma_f32_32x32x16_bf16 v[80:95], v[156:159], v[128:131], v[80:95]
	ds_read_b64_tr_b16 v[234:235], v196 offset:4096
	ds_read_b64_tr_b16 v[238:239], v196 offset:4608
	ds_read_b64_tr_b16 v[242:243], v196 offset:5120
	ds_read_b64_tr_b16 v[156:157], v196 offset:5632
	ds_read_b64_tr_b16 v[236:237], v196 offset:6144
	ds_read_b64_tr_b16 v[240:241], v196 offset:6656
	ds_read_b64_tr_b16 v[244:245], v196 offset:7168
	ds_read_b64_tr_b16 v[158:159], v196 offset:7680
	ds_read_b64_tr_b16 v[148:149], v196 offset:8192
	ds_read_b64_tr_b16 v[124:125], v196 offset:8704
	ds_read_b64_tr_b16 v[108:109], v196 offset:9216
	ds_read_b64_tr_b16 v[100:101], v196 offset:9728
	ds_read_b64_tr_b16 v[150:151], v196 offset:10240
	ds_read_b64_tr_b16 v[126:127], v196 offset:10752
	ds_read_b64_tr_b16 v[110:111], v196 offset:11264
	ds_read_b64_tr_b16 v[102:103], v196 offset:11776
	s_waitcnt lgkmcnt(14)
	v_mfma_f32_32x32x16_bf16 v[64:79], v[226:229], v[128:131], v[64:79]
	v_mfma_f32_32x32x16_bf16 v[0:15], v[144:147], v[104:107], v[0:15]
	v_max3_f32 v104, v80, v81, v82
	v_max3_f32 v104, v104, v83, v84
	v_max3_f32 v104, v104, v85, v86
	v_max3_f32 v104, v104, v87, v88
	v_mfma_f32_32x32x16_bf16 v[48:63], v[144:147], v[120:123], v[48:63]
	v_max3_f32 v104, v104, v89, v90
	v_max3_f32 v104, v104, v91, v92
	v_max3_f32 v104, v104, v93, v94
	s_nop 2
	v_max3_f32 v104, v104, v95, v64
	v_mfma_f32_32x32x16_bf16 v[32:47], v[144:147], v[152:155], v[32:47]
	v_max3_f32 v104, v104, v65, v66
	v_max3_f32 v104, v104, v67, v68
	v_max3_f32 v104, v104, v69, v70
	v_max3_f32 v104, v104, v71, v72
	v_mfma_f32_32x32x16_bf16 v[16:31], v[144:147], v[230:233], v[16:31]
	v_max_f32_e32 v104, v104, v104
	v_max_f32_e32 v105, v73, v73
	v_max_f32_e32 v104, v104, v105
	v_max3_f32 v104, v104, v74, v75
	v_max3_f32 v104, v104, v76, v77
	v_max3_f32 v197, v104, v78, v79
	ds_read_b64_tr_b16 v[152:153], v196 offset:12288
	ds_read_b64_tr_b16 v[144:145], v196 offset:12800
	ds_read_b64_tr_b16 v[120:121], v196 offset:13312
	ds_read_b64_tr_b16 v[104:105], v196 offset:13824
	ds_read_b64_tr_b16 v[154:155], v196 offset:14336
	ds_read_b64_tr_b16 v[146:147], v196 offset:14848
	ds_read_b64_tr_b16 v[122:123], v196 offset:15360
	ds_read_b64_tr_b16 v[106:107], v196 offset:15872
	v_sub_f32_e32 v196, v197, v220
	v_cmp_ge_f32_e32 vcc, s6, v196
	s_cmp_eq_u64 vcc, exec
	s_cbranch_scc0 .Latt_rare_2
	v_mov_b32_e32 v218, v220
	v_mov_b32_e32 v196, v220
	v_mov_b32_e32 v220, 1.0
.Latt_back_2:
	s_waitcnt lgkmcnt(14)
	v_mfma_f32_32x32x16_bf16 v[0:15], v[116:119], v[234:237], v[0:15]
	v_mfma_f32_32x32x16_bf16 v[48:63], v[116:119], v[238:241], v[48:63]
	v_sub_f32_e32 v81, v81, v196
	v_sub_f32_e32 v80, v80, v196
	v_add_f32_e64 v82, v82, -v196
	v_add_f32_e64 v83, v83, -v196
	v_add_f32_e64 v84, v84, -v196
	v_add_f32_e64 v85, v85, -v196
	v_pk_add_f32 v[86:87], v[86:87], v[196:197] op_sel_hi:[1,0] neg_lo:[0,1] neg_hi:[0,1]
	s_nop 0
	v_mfma_f32_32x32x16_bf16 v[32:47], v[116:119], v[242:245], v[32:47]
	v_add_f32_e64 v88, v88, -v196
	v_add_f32_e64 v89, v89, -v196
	v_add_f32_e64 v90, v90, -v196
	v_add_f32_e64 v91, v91, -v196
	v_add_f32_e64 v92, v92, -v196
	v_add_f32_e64 v93, v93, -v196
	v_pk_add_f32 v[94:95], v[94:95], v[196:197] op_sel_hi:[1,0] neg_lo:[0,1] neg_hi:[0,1]
	s_nop 0
	v_mfma_f32_32x32x16_bf16 v[16:31], v[116:119], v[156:159], v[16:31]
	v_sub_f32_e32 v65, v65, v196
	v_sub_f32_e32 v64, v64, v196
	v_add_f32_e64 v66, v66, -v196
	v_add_f32_e64 v67, v67, -v196
	v_add_f32_e64 v68, v68, -v196
	v_add_f32_e64 v69, v69, -v196
	v_pk_add_f32 v[70:71], v[70:71], v[196:197] op_sel_hi:[1,0] neg_lo:[0,1] neg_hi:[0,1]
	s_nop 0
	s_waitcnt lgkmcnt(11)
	v_mfma_f32_32x32x16_bf16 v[0:15], v[112:115], v[148:151], v[0:15]
	v_add_f32_e64 v72, v72, -v196
	v_add_f32_e64 v73, v73, -v196
	v_add_f32_e64 v74, v74, -v196
	v_add_f32_e64 v75, v75, -v196
	v_add_f32_e64 v76, v76, -v196
	v_add_f32_e64 v77, v77, -v196
	v_pk_add_f32 v[78:79], v[78:79], v[196:197] op_sel_hi:[1,0] neg_lo:[0,1] neg_hi:[0,1]
	s_nop 0
	s_waitcnt lgkmcnt(10)
	v_mfma_f32_32x32x16_bf16 v[48:63], v[112:115], v[124:127], v[48:63]
	v_exp_f32_e32 v80, v80
	v_exp_f32_e32 v81, v81
	v_exp_f32_e32 v82, v82
	v_exp_f32_e32 v83, v83
	s_waitcnt lgkmcnt(9)
	v_mfma_f32_32x32x16_bf16 v[32:47], v[112:115], v[108:111], v[32:47]
	v_exp_f32_e32 v84, v84
	v_exp_f32_e32 v85, v85
	v_exp_f32_e32 v86, v86
	v_exp_f32_e32 v87, v87
	s_waitcnt lgkmcnt(8)
	v_mfma_f32_32x32x16_bf16 v[16:31], v[112:115], v[100:103], v[16:31]
	v_exp_f32_e32 v88, v88
	v_exp_f32_e32 v89, v89
	v_exp_f32_e32 v90, v90
	v_exp_f32_e32 v91, v91
	s_waitcnt lgkmcnt(3)
	v_mfma_f32_32x32x16_bf16 v[0:15], v[96:99], v[152:155], v[0:15]
	v_exp_f32_e32 v92, v92
	v_exp_f32_e32 v93, v93
	v_exp_f32_e32 v94, v94
	v_exp_f32_e32 v95, v95
	s_waitcnt lgkmcnt(2)
	v_mfma_f32_32x32x16_bf16 v[48:63], v[96:99], v[144:147], v[48:63]
	v_exp_f32_e32 v64, v64
	v_exp_f32_e32 v65, v65
	v_exp_f32_e32 v66, v66
	v_exp_f32_e32 v67, v67
	v_exp_f32_e32 v68, v68
	s_waitcnt lgkmcnt(1)
	v_mfma_f32_32x32x16_bf16 v[32:47], v[96:99], v[120:123], v[32:47]
	v_exp_f32_e32 v69, v69
	v_exp_f32_e32 v70, v70
	v_exp_f32_e32 v71, v71
	v_exp_f32_e32 v72, v72
	v_exp_f32_e32 v73, v73
	s_waitcnt lgkmcnt(0)
	v_mfma_f32_32x32x16_bf16 v[16:31], v[96:99], v[104:107], v[16:31]
	v_exp_f32_e32 v74, v74
	v_exp_f32_e32 v75, v75
	v_exp_f32_e32 v76, v76
	v_exp_f32_e32 v77, v77
	v_exp_f32_e32 v78, v78
	v_exp_f32_e32 v79, v79
	v_cmp_gt_f32_e32 vcc, 1.0, v220
	s_cbranch_vccz .LBB0_230
	s_and_saveexec_b64 s[20:21], s[38:39]
	ds_write_b32 v182, v220 offset:128
	s_or_b64 exec, exec, s[20:21]
	s_waitcnt lgkmcnt(0)
	v_add_u32_e32 v108, s70, v162
	ds_read_b128 v[96:99], v108 offset:224
	ds_read_b128 v[100:103], v108 offset:192
	ds_read_b128 v[104:107], v108 offset:160
	ds_read_b128 v[108:111], v108 offset:128
	s_waitcnt lgkmcnt(3)
	v_pk_mul_f32 v[12:13], v[12:13], v[96:97]
	s_waitcnt lgkmcnt(2)
	v_pk_mul_f32 v[8:9], v[8:9], v[100:101]
	s_waitcnt lgkmcnt(1)
	v_pk_mul_f32 v[4:5], v[4:5], v[104:105]
	v_pk_mul_f32 v[14:15], v[14:15], v[98:99]
	v_pk_mul_f32 v[10:11], v[10:11], v[102:103]
	v_pk_mul_f32 v[6:7], v[6:7], v[106:107]
	s_waitcnt lgkmcnt(0)
	v_pk_mul_f32 v[2:3], v[2:3], v[110:111]
	v_pk_mul_f32 v[0:1], v[0:1], v[108:109]
	v_pk_mul_f32 v[60:61], v[60:61], v[96:97]
	v_pk_mul_f32 v[56:57], v[56:57], v[100:101]
	v_pk_mul_f32 v[52:53], v[52:53], v[104:105]
	v_pk_mul_f32 v[62:63], v[62:63], v[98:99]
	v_pk_mul_f32 v[58:59], v[58:59], v[102:103]
	v_pk_mul_f32 v[54:55], v[54:55], v[106:107]
	v_pk_mul_f32 v[50:51], v[50:51], v[110:111]
	v_pk_mul_f32 v[48:49], v[48:49], v[108:109]
	v_pk_mul_f32 v[44:45], v[44:45], v[96:97]
	v_pk_mul_f32 v[40:41], v[40:41], v[100:101]
	v_pk_mul_f32 v[36:37], v[36:37], v[104:105]
	v_pk_mul_f32 v[46:47], v[46:47], v[98:99]
	v_pk_mul_f32 v[42:43], v[42:43], v[102:103]
	v_pk_mul_f32 v[38:39], v[38:39], v[106:107]
	v_pk_mul_f32 v[34:35], v[34:35], v[110:111]
	v_pk_mul_f32 v[32:33], v[32:33], v[108:109]
	v_pk_mul_f32 v[28:29], v[28:29], v[96:97]
	v_pk_mul_f32 v[24:25], v[24:25], v[100:101]
	v_pk_mul_f32 v[20:21], v[20:21], v[104:105]
	v_pk_mul_f32 v[30:31], v[30:31], v[98:99]
	v_pk_mul_f32 v[26:27], v[26:27], v[102:103]
	v_pk_mul_f32 v[22:23], v[22:23], v[106:107]
	v_pk_mul_f32 v[18:19], v[18:19], v[110:111]
	v_pk_mul_f32 v[16:17], v[16:17], v[108:109]

.LBB0_234:
	ds_read_b128 v[96:99], v188
	ds_read_b128 v[100:103], v188 offset:8192
	ds_read_b128 v[144:147], v211
	ds_read_b128 v[148:151], v211 offset:8192
	ds_read_b128 v[152:155], v213
	ds_read_b128 v[156:159], v213 offset:8192
	ds_read_b128 v[184:187], v215
	ds_read_b128 v[210:213], v215 offset:8192
	v_add_f32_e32 v104, 0, v80
	v_add_f32_e32 v104, v81, v104
	v_add_f32_e32 v104, v82, v104
	v_add_f32_e32 v104, v83, v104
	v_add_f32_e32 v104, v84, v104
	v_add_f32_e32 v104, v85, v104
	v_add_f32_e32 v104, v86, v104
	v_add_f32_e32 v104, v87, v104
	s_nop 0
	v_add_f32_e32 v104, v88, v104
	s_waitcnt lgkmcnt(7)
	v_mfma_f32_32x32x16_bf16 v[112:127], v[96:99], v[140:143], 0
	v_add_f32_e32 v104, v89, v104
	v_add_f32_e32 v104, v90, v104
	v_add_f32_e32 v104, v91, v104
	v_add_f32_e32 v104, v92, v104
	v_add_f32_e32 v104, v93, v104
	v_add_f32_e32 v104, v94, v104
	v_add_f32_e32 v104, v95, v104
	s_nop 0
	v_add_f32_e32 v96, v64, v104
	v_add_f32_e32 v96, v65, v96
	v_add_f32_e32 v96, v66, v96
	v_add_f32_e32 v96, v67, v96
	v_add_f32_e32 v96, v68, v96
	v_add_f32_e32 v96, v69, v96
	v_add_f32_e32 v96, v70, v96
	v_add_f32_e32 v188, v71, v96
	s_waitcnt lgkmcnt(6)
	v_mfma_f32_32x32x16_bf16 v[96:111], v[100:103], v[140:143], 0
	s_nop 0
	v_add_f32_e32 v140, v72, v188
	s_waitcnt lgkmcnt(5)
	v_mfma_f32_32x32x16_bf16 v[112:127], v[144:147], v[136:139], v[112:127]
	v_add_f32_e32 v140, v73, v140
	v_add_f32_e32 v140, v74, v140
	v_add_f32_e32 v140, v75, v140
	v_add_f32_e32 v140, v76, v140
	v_add_f32_e32 v140, v77, v140
	v_add_f32_e32 v140, v78, v140
	v_add_f32_e32 v140, v79, v140
	v_mov_b32_e32 v144, v140
	v_cvt_pk_bf16_f32 v214, v80, v81
	v_cvt_pk_bf16_f32 v215, v82, v83
	v_cvt_pk_bf16_f32 v216, v84, v85
	v_cvt_pk_bf16_f32 v217, v86, v87
	v_fmac_f32_e32 v144, v219, v220
	v_cvt_pk_bf16_f32 v84, v88, v89
	v_cvt_pk_bf16_f32 v85, v90, v91
	v_cvt_pk_bf16_f32 v86, v92, v93
	v_cvt_pk_bf16_f32 v87, v94, v95
	v_cvt_pk_bf16_f32 v80, v64, v65
	v_cvt_pk_bf16_f32 v81, v66, v67
	v_cvt_pk_bf16_f32 v82, v68, v69
	v_cvt_pk_bf16_f32 v83, v70, v71
	v_cvt_pk_bf16_f32 v64, v72, v73
	v_cvt_pk_bf16_f32 v65, v74, v75
	v_cvt_pk_bf16_f32 v66, v76, v77
	v_cvt_pk_bf16_f32 v67, v78, v79
	s_cmp_lg_u32 0, -1
	s_cselect_b32 s20, 0, 0
	v_add_u32_e32 v145, s20, v183
	v_add_u32_e32 v68, 0x14000, v145
	ds_read_b64_tr_b16 v[72:73], v68
	v_add_u32_e32 v68, 0x14800, v145
	s_waitcnt lgkmcnt(4)
	v_mfma_f32_32x32x16_bf16 v[112:127], v[152:155], v[132:135], v[112:127]
	ds_read_b64_tr_b16 v[74:75], v68
	v_add_u32_e32 v68, 0x14200, v145
	ds_read_b64_tr_b16 v[88:89], v68
	v_add_u32_e32 v68, 0x14a00, v145
	ds_read_b64_tr_b16 v[90:91], v68
	v_add_u32_e32 v68, 0x14400, v145
	ds_read_b64_tr_b16 v[152:153], v68
	v_mfma_f32_32x32x16_bf16 v[96:111], v[148:151], v[136:139], v[96:111]
	v_add_u32_e32 v68, 0x14c00, v145
	ds_read_b64_tr_b16 v[154:155], v68
	v_add_u32_e32 v68, 0x14600, v145
	ds_read_b64_tr_b16 v[220:221], v68
	v_add_u32_e32 v68, 0x14e00, v145
	ds_read_b64_tr_b16 v[222:223], v68
	v_add_u32_e32 v68, 0x15000, v145
	s_waitcnt lgkmcnt(9)
	v_mfma_f32_32x32x16_bf16 v[112:127], v[184:187], v[128:131], v[112:127]
	ds_read_b64_tr_b16 v[184:185], v68
	v_add_u32_e32 v68, 0x15800, v145
	ds_read_b64_tr_b16 v[186:187], v68
	v_add_u32_e32 v68, 0x15200, v145
	ds_read_b64_tr_b16 v[224:225], v68
	v_add_u32_e32 v68, 0x15a00, v145
	ds_read_b64_tr_b16 v[226:227], v68
	v_mfma_f32_32x32x16_bf16 v[96:111], v[156:159], v[132:135], v[96:111]
	v_add_u32_e32 v68, 0x15400, v145
	ds_read_b64_tr_b16 v[146:147], v68
	v_add_u32_e32 v68, 0x15c00, v145
	ds_read_b64_tr_b16 v[148:149], v68
	v_add_u32_e32 v68, 0x15600, v145
	ds_read_b64_tr_b16 v[140:141], v68
	v_add_u32_e32 v68, 0x15e00, v145
	ds_read_b64_tr_b16 v[142:143], v68
	v_add_u32_e32 v68, 0x16000, v145
	ds_read_b64_tr_b16 v[132:133], v68
	v_add_u32_e32 v68, 0x16800, v145
	ds_read_b64_tr_b16 v[134:135], v68
	v_add_u32_e32 v68, 0x16200, v145
	ds_read_b64_tr_b16 v[92:93], v68
	v_add_u32_e32 v68, 0x16a00, v145
	s_waitcnt lgkmcnt(14)
	v_mfma_f32_32x32x16_bf16 v[96:111], v[210:213], v[128:131], v[96:111]
	ds_read_b64_tr_b16 v[94:95], v68
	v_add_u32_e32 v68, 0x16400, v145
	ds_read_b64_tr_b16 v[76:77], v68
	v_add_u32_e32 v68, 0x16c00, v145
	ds_read_b64_tr_b16 v[78:79], v68
	v_add_u32_e32 v68, 0x16600, v145
	v_add_u32_e32 v70, 0x16e00, v145
	ds_read_b64_tr_b16 v[68:69], v68
	ds_read_b64_tr_b16 v[70:71], v70
	v_mfma_f32_32x32x16_bf16 v[0:15], v[214:217], v[72:75], v[0:15]
	v_max3_f32 v72, v112, v113, v114
	v_max3_f32 v72, v72, v115, v116
	v_max3_f32 v72, v72, v117, v118
	v_max3_f32 v72, v72, v119, v120
	v_mfma_f32_32x32x16_bf16 v[48:63], v[214:217], v[88:91], v[48:63]
	v_max3_f32 v72, v72, v121, v122
	v_max3_f32 v72, v72, v123, v124
	v_max3_f32 v72, v72, v125, v126
	v_max3_f32 v72, v72, v127, v96
	s_waitcnt lgkmcnt(14)
	v_mfma_f32_32x32x16_bf16 v[32:47], v[214:217], v[152:155], v[32:47]
	v_max3_f32 v72, v72, v97, v98
	v_max3_f32 v72, v72, v99, v100
	v_max3_f32 v72, v72, v101, v102
	v_max3_f32 v72, v72, v103, v104
	v_mfma_f32_32x32x16_bf16 v[16:31], v[214:217], v[220:223], v[16:31]
	v_max_f32_e32 v72, v72, v72
	v_max_f32_e32 v73, v105, v105
	v_max_f32_e32 v72, v72, v73
	v_max3_f32 v72, v72, v106, v107
	v_max3_f32 v72, v72, v108, v109
	v_max3_f32 v150, v72, v110, v111
	v_add_u32_e32 v72, 0x17000, v145
	ds_read_b64_tr_b16 v[136:137], v72
	v_add_u32_e32 v72, 0x17800, v145
	ds_read_b64_tr_b16 v[138:139], v72
	v_add_u32_e32 v72, 0x17200, v145
	ds_read_b64_tr_b16 v[128:129], v72
	v_add_u32_e32 v72, 0x17a00, v145
	ds_read_b64_tr_b16 v[130:131], v72
	v_add_u32_e32 v72, 0x17400, v145
	ds_read_b64_tr_b16 v[88:89], v72
	v_add_u32_e32 v72, 0x17c00, v145
	ds_read_b64_tr_b16 v[90:91], v72
	v_add_u32_e32 v72, 0x17600, v145
	v_add_u32_e32 v74, 0x17e00, v145
	ds_read_b64_tr_b16 v[72:73], v72
	ds_read_b64_tr_b16 v[74:75], v74
	v_sub_f32_e32 v145, v150, v218
	v_cmp_ge_f32_e32 vcc, s6, v145
	s_cmp_eq_u64 vcc, exec
	s_cbranch_scc0 .Latt_rare_3
	v_mov_b32_e32 v150, v218
	v_mov_b32_e32 v145, 1.0
.Latt_back_3:
	v_mfma_f32_32x32x16_bf16 v[0:15], v[84:87], v[184:187], v[0:15]
	s_waitcnt lgkmcnt(14)
	v_mfma_f32_32x32x16_bf16 v[48:63], v[84:87], v[224:227], v[48:63]
	v_sub_f32_e32 v113, v113, v150
	v_sub_f32_e32 v112, v112, v150
	v_add_f32_e64 v114, v114, -v150
	v_add_f32_e64 v115, v115, -v150
	v_add_f32_e64 v116, v116, -v150
	v_add_f32_e64 v117, v117, -v150
	v_pk_add_f32 v[118:119], v[118:119], v[150:151] op_sel_hi:[1,0] neg_lo:[0,1] neg_hi:[0,1]
	s_nop 0
	v_mfma_f32_32x32x16_bf16 v[32:47], v[84:87], v[146:149], v[32:47]
	v_add_f32_e64 v120, v120, -v150
	v_add_f32_e64 v121, v121, -v150
	v_add_f32_e64 v122, v122, -v150
	v_add_f32_e64 v123, v123, -v150
	v_add_f32_e64 v124, v124, -v150
	v_add_f32_e64 v125, v125, -v150
	v_pk_add_f32 v[126:127], v[126:127], v[150:151] op_sel_hi:[1,0] neg_lo:[0,1] neg_hi:[0,1]
	s_nop 0
	v_mfma_f32_32x32x16_bf16 v[16:31], v[84:87], v[140:143], v[16:31]
	v_sub_f32_e32 v97, v97, v150
	v_sub_f32_e32 v96, v96, v150
	v_add_f32_e64 v98, v98, -v150
	v_add_f32_e64 v99, v99, -v150
	v_add_f32_e64 v100, v100, -v150
	v_add_f32_e64 v101, v101, -v150
	v_pk_add_f32 v[102:103], v[102:103], v[150:151] op_sel_hi:[1,0] neg_lo:[0,1] neg_hi:[0,1]
	s_nop 0
	v_mfma_f32_32x32x16_bf16 v[0:15], v[80:83], v[132:135], v[0:15]
	v_add_f32_e64 v104, v104, -v150
	v_add_f32_e64 v105, v105, -v150
	v_add_f32_e64 v106, v106, -v150
	v_add_f32_e64 v107, v107, -v150
	v_add_f32_e64 v108, v108, -v150
	v_add_f32_e64 v109, v109, -v150
	v_pk_add_f32 v[110:111], v[110:111], v[150:151] op_sel_hi:[1,0] neg_lo:[0,1] neg_hi:[0,1]
	s_nop 0
	s_waitcnt lgkmcnt(12)
	v_mfma_f32_32x32x16_bf16 v[48:63], v[80:83], v[92:95], v[48:63]
	v_exp_f32_e32 v112, v112
	v_exp_f32_e32 v113, v113
	v_exp_f32_e32 v114, v114
	v_exp_f32_e32 v115, v115
	s_waitcnt lgkmcnt(10)
	v_mfma_f32_32x32x16_bf16 v[32:47], v[80:83], v[76:79], v[32:47]
	v_exp_f32_e32 v116, v116
	v_exp_f32_e32 v117, v117
	v_exp_f32_e32 v118, v118
	v_exp_f32_e32 v119, v119
	s_waitcnt lgkmcnt(8)
	v_mfma_f32_32x32x16_bf16 v[16:31], v[80:83], v[68:71], v[16:31]
	v_exp_f32_e32 v120, v120
	v_exp_f32_e32 v121, v121
	v_exp_f32_e32 v122, v122
	v_exp_f32_e32 v123, v123
	s_waitcnt lgkmcnt(6)
	v_mfma_f32_32x32x16_bf16 v[0:15], v[64:67], v[136:139], v[0:15]
	v_exp_f32_e32 v124, v124
	v_exp_f32_e32 v125, v125
	v_exp_f32_e32 v126, v126
	v_exp_f32_e32 v127, v127
	s_waitcnt lgkmcnt(4)
	v_mfma_f32_32x32x16_bf16 v[48:63], v[64:67], v[128:131], v[48:63]
	v_exp_f32_e32 v96, v96
	v_exp_f32_e32 v97, v97
	v_exp_f32_e32 v98, v98
	v_exp_f32_e32 v99, v99
	v_exp_f32_e32 v100, v100
	s_waitcnt lgkmcnt(2)
	v_mfma_f32_32x32x16_bf16 v[32:47], v[64:67], v[88:91], v[32:47]
	v_exp_f32_e32 v101, v101
	v_exp_f32_e32 v102, v102
	v_exp_f32_e32 v103, v103
	v_exp_f32_e32 v104, v104
	v_exp_f32_e32 v105, v105
	s_waitcnt lgkmcnt(0)
	v_mfma_f32_32x32x16_bf16 v[16:31], v[64:67], v[72:75], v[16:31]
	v_exp_f32_e32 v106, v106
	v_exp_f32_e32 v107, v107
	v_exp_f32_e32 v108, v108
	v_exp_f32_e32 v109, v109
	v_exp_f32_e32 v110, v110
	v_exp_f32_e32 v111, v111
	v_cmp_gt_f32_e32 vcc, 1.0, v145
	s_cbranch_vccz .LBB0_238
	s_and_saveexec_b64 s[20:21], s[38:39]
	ds_write_b32 v182, v145 offset:128
	s_or_b64 exec, exec, s[20:21]
	s_waitcnt lgkmcnt(0)
	v_add_u32_e32 v76, s70, v162
	ds_read_b128 v[64:67], v76 offset:224
	ds_read_b128 v[68:71], v76 offset:192
	ds_read_b128 v[72:75], v76 offset:160
	ds_read_b128 v[76:79], v76 offset:128
	s_waitcnt lgkmcnt(3)
	v_pk_mul_f32 v[12:13], v[12:13], v[64:65]
	s_waitcnt lgkmcnt(2)
	v_pk_mul_f32 v[8:9], v[8:9], v[68:69]
	s_waitcnt lgkmcnt(1)
	v_pk_mul_f32 v[4:5], v[4:5], v[72:73]
	v_pk_mul_f32 v[14:15], v[14:15], v[66:67]
	v_pk_mul_f32 v[10:11], v[10:11], v[70:71]
	v_pk_mul_f32 v[6:7], v[6:7], v[74:75]
	s_waitcnt lgkmcnt(0)
	v_pk_mul_f32 v[2:3], v[2:3], v[78:79]
	v_pk_mul_f32 v[0:1], v[0:1], v[76:77]
	v_pk_mul_f32 v[60:61], v[60:61], v[64:65]
	v_pk_mul_f32 v[56:57], v[56:57], v[68:69]
	v_pk_mul_f32 v[52:53], v[52:53], v[72:73]
	v_pk_mul_f32 v[62:63], v[62:63], v[66:67]
	v_pk_mul_f32 v[58:59], v[58:59], v[70:71]
	v_pk_mul_f32 v[54:55], v[54:55], v[74:75]
	v_pk_mul_f32 v[50:51], v[50:51], v[78:79]
	v_pk_mul_f32 v[48:49], v[48:49], v[76:77]
	v_pk_mul_f32 v[44:45], v[44:45], v[64:65]
	v_pk_mul_f32 v[40:41], v[40:41], v[68:69]
	v_pk_mul_f32 v[36:37], v[36:37], v[72:73]
	v_pk_mul_f32 v[46:47], v[46:47], v[66:67]
	v_pk_mul_f32 v[42:43], v[42:43], v[70:71]
	v_pk_mul_f32 v[38:39], v[38:39], v[74:75]
	v_pk_mul_f32 v[34:35], v[34:35], v[78:79]
	v_pk_mul_f32 v[32:33], v[32:33], v[76:77]
	v_pk_mul_f32 v[28:29], v[28:29], v[64:65]
	v_pk_mul_f32 v[24:25], v[24:25], v[68:69]
	v_pk_mul_f32 v[20:21], v[20:21], v[72:73]
	v_pk_mul_f32 v[30:31], v[30:31], v[66:67]
	v_pk_mul_f32 v[26:27], v[26:27], v[70:71]
	v_pk_mul_f32 v[22:23], v[22:23], v[74:75]
	v_pk_mul_f32 v[18:19], v[18:19], v[78:79]
	v_pk_mul_f32 v[16:17], v[16:17], v[76:77]
; #define SBAR() __builtin_amdgcn_sched_barrier(0)
; __device__ __forceinline__ int crow(int r, int hi) { return (r & 3) + 8 * (r >> 2) + 4 * hi; }
; __device__ __forceinline__ void attn_unit(const bf16* __restrict__ proj, bf16* __restrict__ cat, int b, int h, int qb, float lam, float oscale, const float* __restrict__ subln, const float* __restrict__ cw, char* lds) {
;     ...
;   { float ps = 0.f;
; #pragma unroll
;     for (int r = 0; r < 16; ++r) ps += pB0[r];
; #pragma unroll
;     for (int r = 0; r < 16; ++r) ps += pB1[r];
;     { auto rr = __builtin_amdgcn_permlane32_swap(__float_as_uint(ps), __float_as_uint(ps), false, false); ps = __uint_as_float(rr[0]) + __uint_as_float(rr[1]); }
;     l_reg = l_reg * alB + ps; PK4(pB0, 0, pa0); PK4(pB0, 8, pa1); PK4(pB1, 0, pa2); PK4(pB1, 8, pa3); }
;   SBAR();
;   pv_d0(o, vb0 + ((sj == 0) ? 2 : sj - 1) * SHM_V, pa0, pa1, pa2, pa3);
;   if (hi == 0) li_l[r32] = l_reg; asm volatile("s_waitcnt lgkmcnt(0)" ::: "memory");
;   float rli[16];
; #pragma unroll
;   for (int r = 0; r < 16; ++r) rli[r] = __builtin_amdgcn_rcpf(li_l[crow(r, hi)]);
;   __syncthreads();
.LBB0_238:
	v_add_f32_e32 v64, 0, v112
	v_add_f32_e32 v64, v113, v64
	v_add_f32_e32 v64, v114, v64
	v_add_f32_e32 v64, v115, v64
	v_add_f32_e32 v64, v116, v64
	v_add_f32_e32 v64, v117, v64
	v_add_f32_e32 v64, v118, v64
	v_add_f32_e32 v64, v119, v64
	v_add_f32_e32 v64, v120, v64
	v_add_f32_e32 v64, v121, v64
	v_add_f32_e32 v64, v122, v64
	v_add_f32_e32 v64, v123, v64
	v_add_f32_e32 v64, v124, v64
	v_add_f32_e32 v64, v125, v64
	v_add_f32_e32 v64, v126, v64
	v_add_f32_e32 v64, v127, v64
	v_add_f32_e32 v64, v96, v64
	v_add_f32_e32 v64, v97, v64
	v_add_f32_e32 v64, v98, v64
	v_add_f32_e32 v64, v99, v64
	v_add_f32_e32 v64, v100, v64
	v_add_f32_e32 v64, v101, v64
	v_add_f32_e32 v64, v102, v64
	v_add_f32_e32 v64, v103, v64
	v_add_f32_e32 v64, v104, v64
	v_add_f32_e32 v64, v105, v64
	v_add_f32_e32 v64, v106, v64
	v_add_f32_e32 v64, v107, v64
	v_add_f32_e32 v64, v108, v64
	v_add_f32_e32 v64, v109, v64
	v_add_f32_e32 v64, v110, v64
	s_waitcnt vmcnt(0) lgkmcnt(0)
	s_barrier
	v_add_f32_e32 v72, v111, v64
	v_fmac_f32_e32 v72, v144, v145
	v_mov_b32_e32 v73, v72
	s_nop 1
	v_permlane32_swap_b32_e32 v72, v73
	v_cvt_pk_bf16_f32 v74, v112, v113
	v_cvt_pk_bf16_f32 v75, v114, v115
	v_cvt_pk_bf16_f32 v76, v116, v117
	v_cvt_pk_bf16_f32 v77, v118, v119
	v_cvt_pk_bf16_f32 v78, v120, v121
	v_cvt_pk_bf16_f32 v79, v122, v123
	v_cvt_pk_bf16_f32 v80, v124, v125
	v_cvt_pk_bf16_f32 v81, v126, v127
	v_cvt_pk_bf16_f32 v68, v96, v97
	v_cvt_pk_bf16_f32 v69, v98, v99
	v_cvt_pk_bf16_f32 v70, v100, v101
	v_cvt_pk_bf16_f32 v71, v102, v103
	v_cvt_pk_bf16_f32 v64, v104, v105
	v_cvt_pk_bf16_f32 v65, v106, v107
	v_cvt_pk_bf16_f32 v66, v108, v109
	v_cvt_pk_bf16_f32 v67, v110, v111
	s_cmp_lg_u32 0, -1
	s_cselect_b32 s20, 0, 0
	v_add_u32_e32 v82, 0, v183
	v_add_u32_e32 v86, s20, v183
	ds_read_b64_tr_b16 v[82:83], v82 offset:49152
	ds_read_b64_tr_b16 v[84:85], v86 offset:51200
	s_waitcnt lgkmcnt(0)
	v_mfma_f32_32x32x16_bf16 v[0:15], v[74:77], v[82:85], v[0:15]
	ds_read_b64_tr_b16 v[84:85], v86 offset:51712
	ds_read_b64_tr_b16 v[82:83], v86 offset:49664
	s_waitcnt lgkmcnt(0)
	v_mfma_f32_32x32x16_bf16 v[48:63], v[74:77], v[82:85], v[48:63]
	ds_read_b64_tr_b16 v[82:83], v86 offset:50176
	ds_read_b64_tr_b16 v[84:85], v86 offset:52224
	s_waitcnt lgkmcnt(0)
	v_mfma_f32_32x32x16_bf16 v[32:47], v[74:77], v[82:85], v[32:47]
	ds_read_b64_tr_b16 v[82:83], v86 offset:50688
	ds_read_b64_tr_b16 v[84:85], v86 offset:52736
	s_waitcnt lgkmcnt(0)
	v_mfma_f32_32x32x16_bf16 v[16:31], v[74:77], v[82:85], v[16:31]
	ds_read_b64_tr_b16 v[74:75], v86 offset:53248
	ds_read_b64_tr_b16 v[76:77], v86 offset:55296
	s_waitcnt lgkmcnt(0)
	v_mfma_f32_32x32x16_bf16 v[0:15], v[78:81], v[74:77], v[0:15]
	ds_read_b64_tr_b16 v[76:77], v86 offset:55808
	ds_read_b64_tr_b16 v[74:75], v86 offset:53760
	s_waitcnt lgkmcnt(0)
	v_mfma_f32_32x32x16_bf16 v[48:63], v[78:81], v[74:77], v[48:63]
	ds_read_b64_tr_b16 v[74:75], v86 offset:54272
	ds_read_b64_tr_b16 v[76:77], v86 offset:56320
	s_waitcnt lgkmcnt(0)
	v_mfma_f32_32x32x16_bf16 v[32:47], v[78:81], v[74:77], v[32:47]
	ds_read_b64_tr_b16 v[74:75], v86 offset:54784
	ds_read_b64_tr_b16 v[76:77], v86 offset:56832
	s_waitcnt lgkmcnt(0)
	v_mfma_f32_32x32x16_bf16 v[16:31], v[78:81], v[74:77], v[16:31]
	ds_read_b64_tr_b16 v[74:75], v86 offset:57344
	ds_read_b64_tr_b16 v[76:77], v86 offset:59392
	s_waitcnt lgkmcnt(0)
	v_mfma_f32_32x32x16_bf16 v[0:15], v[68:71], v[74:77], v[0:15]
	ds_read_b64_tr_b16 v[76:77], v86 offset:59904
	ds_read_b64_tr_b16 v[74:75], v86 offset:57856
	s_waitcnt lgkmcnt(0)
	v_mfma_f32_32x32x16_bf16 v[48:63], v[68:71], v[74:77], v[48:63]
	ds_read_b64_tr_b16 v[74:75], v86 offset:58368
	ds_read_b64_tr_b16 v[76:77], v86 offset:60416
	s_waitcnt lgkmcnt(0)
	v_mfma_f32_32x32x16_bf16 v[32:47], v[68:71], v[74:77], v[32:47]
	ds_read_b64_tr_b16 v[74:75], v86 offset:58880
	ds_read_b64_tr_b16 v[76:77], v86 offset:60928
	s_waitcnt lgkmcnt(0)
	v_mfma_f32_32x32x16_bf16 v[16:31], v[68:71], v[74:77], v[16:31]
	ds_read_b64_tr_b16 v[68:69], v86 offset:61440
	ds_read_b64_tr_b16 v[70:71], v86 offset:63488
	s_waitcnt lgkmcnt(0)
	v_mfma_f32_32x32x16_bf16 v[0:15], v[64:67], v[68:71], v[0:15]
	ds_read_b64_tr_b16 v[70:71], v86 offset:64000
	ds_read_b64_tr_b16 v[68:69], v86 offset:61952
	s_waitcnt lgkmcnt(0)
	v_mfma_f32_32x32x16_bf16 v[48:63], v[64:67], v[68:71], v[48:63]
	ds_read_b64_tr_b16 v[68:69], v86 offset:62464
	ds_read_b64_tr_b16 v[70:71], v86 offset:64512
	s_waitcnt lgkmcnt(0)
	v_mfma_f32_32x32x16_bf16 v[32:47], v[64:67], v[68:71], v[32:47]
	ds_read_b64_tr_b16 v[68:69], v86 offset:62976
	ds_read_b64_tr_b16 v[70:71], v86 offset:65024
	s_waitcnt lgkmcnt(0)
	v_mfma_f32_32x32x16_bf16 v[16:31], v[64:67], v[68:71], v[16:31]
	s_and_saveexec_b64 s[20:21], s[38:39]
	v_add_f32_e32 v64, v72, v73
	ds_write_b32 v182, v64
	s_or_b64 exec, exec, s[20:21]
	s_waitcnt lgkmcnt(0)
	v_add_u32_e32 v72, s70, v162
	ds_read_b128 v[64:67], v72
	ds_read_b128 v[68:71], v72 offset:32
	s_lshl_b32 s20, s25, 14
	s_add_i32 s20, s20, 0
	s_cmp_lg_u32 s24, 1
	s_waitcnt lgkmcnt(1)
	v_rcp_f32_e32 v150, v64
	v_rcp_f32_e32 v149, v65
	v_rcp_f32_e32 v148, v66
	v_rcp_f32_e32 v147, v67
	s_waitcnt lgkmcnt(0)
	v_rcp_f32_e32 v146, v68
	ds_read_b128 v[64:67], v72 offset:64
	v_rcp_f32_e32 v145, v69
	v_rcp_f32_e32 v144, v70
	v_rcp_f32_e32 v143, v71
	ds_read_b128 v[68:71], v72 offset:96
	s_waitcnt lgkmcnt(1)
	v_rcp_f32_e32 v142, v64
	v_rcp_f32_e32 v141, v65
	v_rcp_f32_e32 v140, v66
	v_rcp_f32_e32 v139, v67
	s_waitcnt lgkmcnt(0)
	v_rcp_f32_e32 v138, v68
	v_rcp_f32_e32 v137, v69
	v_rcp_f32_e32 v135, v70
	v_rcp_f32_e32 v134, v71
	v_lshl_add_u32 v136, v177, 2, s20
	s_barrier
	s_cbranch_scc1 .LBB0_242
; __device__ __forceinline__ void attn_unit(const bf16* __restrict__ proj, bf16* __restrict__ cat, int b, int h, int qb, float lam, float oscale, const float* __restrict__ subln, const float* __restrict__ cw, char* lds) {
;     ...
;   float* X = (float*)(lds + rg * 16384);
;   if (mp == 1) {
; #pragma unroll
;     for (int d0 = 0; d0 < 4; ++d0)
; #pragma unroll
;       for (int r = 0; r < 16; ++r) X[(d0 * 16 + r) * 64 + lane] = o[d0][r] * rli[r] * lam;
;   }
	v_mul_f32_e32 v64, v0, v150
	v_mul_f32_e32 v65, v1, v149
	v_mul_f32_e32 v64, v176, v64
	v_mul_f32_e32 v65, v176, v65
	ds_write2st64_b32 v136, v64, v65 offset1:1
	v_mul_f32_e32 v64, v2, v148
	v_mul_f32_e32 v65, v3, v147
	v_mul_f32_e32 v64, v176, v64
	v_mul_f32_e32 v65, v176, v65
	ds_write2st64_b32 v136, v64, v65 offset0:2 offset1:3
	v_mul_f32_e32 v64, v4, v146
	v_mul_f32_e32 v65, v5, v145
	v_mul_f32_e32 v64, v176, v64
	v_mul_f32_e32 v65, v176, v65
	ds_write2st64_b32 v136, v64, v65 offset0:4 offset1:5
	v_mul_f32_e32 v64, v6, v144
	v_mul_f32_e32 v65, v7, v143
	v_mul_f32_e32 v64, v176, v64
	v_mul_f32_e32 v65, v176, v65
	ds_write2st64_b32 v136, v64, v65 offset0:6 offset1:7
	v_mul_f32_e32 v64, v8, v142
	v_mul_f32_e32 v65, v9, v141
	v_mul_f32_e32 v64, v176, v64
	v_mul_f32_e32 v65, v176, v65
	ds_write2st64_b32 v136, v64, v65 offset0:8 offset1:9
	v_mul_f32_e32 v64, v10, v140
	v_mul_f32_e32 v65, v11, v139
	v_mul_f32_e32 v64, v176, v64
	v_mul_f32_e32 v65, v176, v65
	ds_write2st64_b32 v136, v64, v65 offset0:10 offset1:11
	v_mul_f32_e32 v64, v12, v138
	v_mul_f32_e32 v65, v13, v137
	v_mul_f32_e32 v64, v176, v64
	v_mul_f32_e32 v65, v176, v65
	ds_write2st64_b32 v136, v64, v65 offset0:12 offset1:13
	v_mul_f32_e32 v64, v14, v135
	v_mul_f32_e32 v65, v15, v134
	v_mul_f32_e32 v64, v176, v64
	v_mul_f32_e32 v65, v176, v65
	ds_write2st64_b32 v136, v64, v65 offset0:14 offset1:15
	v_mul_f32_e32 v64, v48, v150
	v_mul_f32_e32 v65, v49, v149
	v_mul_f32_e32 v64, v176, v64
	v_mul_f32_e32 v65, v176, v65
	ds_write2st64_b32 v136, v64, v65 offset0:16 offset1:17
	v_mul_f32_e32 v64, v50, v148
	v_mul_f32_e32 v65, v51, v147
	v_mul_f32_e32 v64, v176, v64
	v_mul_f32_e32 v65, v176, v65
	ds_write2st64_b32 v136, v64, v65 offset0:18 offset1:19
	v_mul_f32_e32 v64, v52, v146
	v_mul_f32_e32 v65, v53, v145
	v_mul_f32_e32 v64, v176, v64
	v_mul_f32_e32 v65, v176, v65
	ds_write2st64_b32 v136, v64, v65 offset0:20 offset1:21
	v_mul_f32_e32 v64, v54, v144
	v_mul_f32_e32 v65, v55, v143
	v_mul_f32_e32 v64, v176, v64
	v_mul_f32_e32 v65, v176, v65
	ds_write2st64_b32 v136, v64, v65 offset0:22 offset1:23
	v_mul_f32_e32 v64, v56, v142
	v_mul_f32_e32 v65, v57, v141
	v_mul_f32_e32 v64, v176, v64
	v_mul_f32_e32 v65, v176, v65
	ds_write2st64_b32 v136, v64, v65 offset0:24 offset1:25
	v_mul_f32_e32 v64, v58, v140
	v_mul_f32_e32 v65, v59, v139
	v_mul_f32_e32 v64, v176, v64
	v_mul_f32_e32 v65, v176, v65
	ds_write2st64_b32 v136, v64, v65 offset0:26 offset1:27
	v_mul_f32_e32 v64, v60, v138
	v_mul_f32_e32 v65, v61, v137
	v_mul_f32_e32 v64, v176, v64
	v_mul_f32_e32 v65, v176, v65
	ds_write2st64_b32 v136, v64, v65 offset0:28 offset1:29
	v_mul_f32_e32 v64, v62, v135
	v_mul_f32_e32 v65, v63, v134
	v_mul_f32_e32 v64, v176, v64
	v_mul_f32_e32 v65, v176, v65
	ds_write2st64_b32 v136, v64, v65 offset0:30 offset1:31
	v_mul_f32_e32 v64, v32, v150
	v_mul_f32_e32 v65, v33, v149
	v_mul_f32_e32 v64, v176, v64
	v_mul_f32_e32 v65, v176, v65
	ds_write2st64_b32 v136, v64, v65 offset0:32 offset1:33
	v_mul_f32_e32 v64, v34, v148
	v_mul_f32_e32 v65, v35, v147
	v_mul_f32_e32 v64, v176, v64
	v_mul_f32_e32 v65, v176, v65
	ds_write2st64_b32 v136, v64, v65 offset0:34 offset1:35
	v_mul_f32_e32 v64, v36, v146
	v_mul_f32_e32 v65, v37, v145
	v_mul_f32_e32 v64, v176, v64
	v_mul_f32_e32 v65, v176, v65
	ds_write2st64_b32 v136, v64, v65 offset0:36 offset1:37
	v_mul_f32_e32 v64, v38, v144
	v_mul_f32_e32 v65, v39, v143
	v_mul_f32_e32 v64, v176, v64
	v_mul_f32_e32 v65, v176, v65
	ds_write2st64_b32 v136, v64, v65 offset0:38 offset1:39
	v_mul_f32_e32 v64, v40, v142
	v_mul_f32_e32 v65, v41, v141
	v_mul_f32_e32 v64, v176, v64
	v_mul_f32_e32 v65, v176, v65
	ds_write2st64_b32 v136, v64, v65 offset0:40 offset1:41
	v_mul_f32_e32 v64, v42, v140
	v_mul_f32_e32 v65, v43, v139
	v_mul_f32_e32 v64, v176, v64
	v_mul_f32_e32 v65, v176, v65
	ds_write2st64_b32 v136, v64, v65 offset0:42 offset1:43
	v_mul_f32_e32 v64, v44, v138
	v_mul_f32_e32 v65, v45, v137
	v_mul_f32_e32 v64, v176, v64
	v_mul_f32_e32 v65, v176, v65
	ds_write2st64_b32 v136, v64, v65 offset0:44 offset1:45
	v_mul_f32_e32 v64, v46, v135
	v_mul_f32_e32 v65, v47, v134
	v_mul_f32_e32 v64, v176, v64
	v_mul_f32_e32 v65, v176, v65
	ds_write2st64_b32 v136, v64, v65 offset0:46 offset1:47
	v_mul_f32_e32 v64, v16, v150
	v_mul_f32_e32 v65, v17, v149
	v_mul_f32_e32 v64, v176, v64
	v_mul_f32_e32 v65, v176, v65
	ds_write2st64_b32 v136, v64, v65 offset0:48 offset1:49
	v_mul_f32_e32 v64, v18, v148
	v_mul_f32_e32 v65, v19, v147
	v_mul_f32_e32 v64, v176, v64
	v_mul_f32_e32 v65, v176, v65
	ds_write2st64_b32 v136, v64, v65 offset0:50 offset1:51
	v_mul_f32_e32 v64, v20, v146
	v_mul_f32_e32 v65, v21, v145
	v_mul_f32_e32 v64, v176, v64
	v_mul_f32_e32 v65, v176, v65
	ds_write2st64_b32 v136, v64, v65 offset0:52 offset1:53
	v_mul_f32_e32 v64, v22, v144
	v_mul_f32_e32 v65, v23, v143
	v_mul_f32_e32 v64, v176, v64
	v_mul_f32_e32 v65, v176, v65
	ds_write2st64_b32 v136, v64, v65 offset0:54 offset1:55
	v_mul_f32_e32 v64, v24, v142
	v_mul_f32_e32 v65, v25, v141
	v_mul_f32_e32 v64, v176, v64
	v_mul_f32_e32 v65, v176, v65
	ds_write2st64_b32 v136, v64, v65 offset0:56 offset1:57
	v_mul_f32_e32 v64, v26, v140
	v_mul_f32_e32 v65, v27, v139
	v_mul_f32_e32 v64, v176, v64
	v_mul_f32_e32 v65, v176, v65
	ds_write2st64_b32 v136, v64, v65 offset0:58 offset1:59
	v_mul_f32_e32 v64, v28, v138
	v_mul_f32_e32 v65, v29, v137
	v_mul_f32_e32 v64, v176, v64
	v_mul_f32_e32 v65, v176, v65
	ds_write2st64_b32 v136, v64, v65 offset0:60 offset1:61
	v_mul_f32_e32 v64, v30, v135
	v_mul_f32_e32 v65, v31, v134
	v_mul_f32_e32 v64, v176, v64
	v_mul_f32_e32 v65, v176, v65
	ds_write2st64_b32 v136, v64, v65 offset0:62 offset1:63

.Latt_rare_1:
	v_mov_b32_e32 v196, v197
	s_nop 1
	v_permlane32_swap_b32_e32 v197, v196
	v_max_f32_e32 v196, v196, v196
	v_max_f32_e32 v197, v197, v197
	v_max_f32_e32 v196, v197, v196
	v_max_f32_e32 v197, v218, v218
	v_max_f32_e32 v196, v197, v196
	v_sub_f32_e32 v197, v218, v196
	v_mov_b32_e32 v220, v196
	v_exp_f32_e32 v218, v197
	s_branch .Latt_back_1
.Latt_rare_2:
	v_mov_b32_e32 v196, v197
	s_nop 1
	v_permlane32_swap_b32_e32 v197, v196
	v_max_f32_e32 v196, v196, v196
	v_max_f32_e32 v197, v197, v197
	v_max_f32_e32 v196, v197, v196
	v_max_f32_e32 v197, v220, v220
	v_max_f32_e32 v196, v197, v196
	v_sub_f32_e32 v197, v220, v196
	v_mov_b32_e32 v218, v196
	v_exp_f32_e32 v220, v197
	s_branch .Latt_back_2
.Latt_rare_3:
	v_mov_b32_e32 v145, v150
	s_nop 1
	v_permlane32_swap_b32_e32 v150, v145
	v_max_f32_e32 v145, v145, v145
	v_max_f32_e32 v150, v150, v150
	v_max_f32_e32 v145, v150, v145
	v_max_f32_e32 v150, v218, v218
	v_max_f32_e32 v150, v150, v145
	v_sub_f32_e32 v145, v218, v150
	v_exp_f32_e32 v145, v145
	s_branch .Latt_back_3
